# prologue de-serialisation: P0 silu(c) staging loop and P1 gate-column preload issue all their loads up front behind counted waits
# speedup vs baseline: 1.0047x; 1.0014x over previous
.LBB0_33:
	s_and_saveexec_b64 s[38:39], vcc
	s_cbranch_execz .LBB0_36
	v_mov_b64_e32 v[0:1], v[130:131]
	global_load_dword v4, v[0:1], off
	global_load_dword v5, v[0:1], off offset:2048
	v_lshl_add_u64 v[0:1], v[0:1], 0, s[34:35]
	v_lshl_add_u64 v[0:1], v[0:1], 0, s[34:35]
	global_load_dword v6, v[0:1], off
	global_load_dword v7, v[0:1], off offset:2048
	v_lshl_add_u64 v[0:1], v[0:1], 0, s[34:35]
	v_lshl_add_u64 v[0:1], v[0:1], 0, s[34:35]
	global_load_dword v8, v[0:1], off
	global_load_dword v9, v[0:1], off offset:2048
	v_lshl_add_u64 v[0:1], v[0:1], 0, s[34:35]
	v_lshl_add_u64 v[0:1], v[0:1], 0, s[34:35]
	global_load_dword v10, v[0:1], off
	global_load_dword v11, v[0:1], off offset:2048
	v_lshl_add_u64 v[0:1], v[0:1], 0, s[34:35]
	v_lshl_add_u64 v[0:1], v[0:1], 0, s[34:35]
	global_load_dword v12, v[0:1], off
	global_load_dword v13, v[0:1], off offset:2048
	v_lshl_add_u64 v[0:1], v[0:1], 0, s[34:35]
	v_lshl_add_u64 v[0:1], v[0:1], 0, s[34:35]
	global_load_dword v14, v[0:1], off
	global_load_dword v15, v[0:1], off offset:2048
	v_lshl_add_u64 v[0:1], v[0:1], 0, s[34:35]
	v_lshl_add_u64 v[0:1], v[0:1], 0, s[34:35]
	global_load_dword v16, v[0:1], off
	global_load_dword v17, v[0:1], off offset:2048
	v_lshl_add_u64 v[0:1], v[0:1], 0, s[34:35]
	v_lshl_add_u64 v[0:1], v[0:1], 0, s[34:35]
	global_load_dword v18, v[0:1], off
	global_load_dword v19, v[0:1], off offset:2048
	s_waitcnt vmcnt(14)
	v_mul_f32_e32 v22, 0xbfb8aa3b, v4
	v_mul_f32_e32 v23, 0xbfb8aa3b, v5
	v_exp_f32_e32 v22, v22
	v_exp_f32_e32 v23, v23
	s_nop 0
	v_add_f32_e32 v22, 1.0, v22
	v_add_f32_e32 v23, 1.0, v23
	v_rcp_f32_e32 v22, v22
	v_rcp_f32_e32 v23, v23
	s_nop 0
	v_mul_f32_e32 v4, v4, v22
	v_mul_f32_e32 v5, v5, v23
	ds_write_b32 v152, v4 offset:0
	ds_write_b32 v152, v5 offset:2048
	s_waitcnt vmcnt(12)
	v_mul_f32_e32 v22, 0xbfb8aa3b, v6
	v_mul_f32_e32 v23, 0xbfb8aa3b, v7
	v_exp_f32_e32 v22, v22
	v_exp_f32_e32 v23, v23
	s_nop 0
	v_add_f32_e32 v22, 1.0, v22
	v_add_f32_e32 v23, 1.0, v23
	v_rcp_f32_e32 v22, v22
	v_rcp_f32_e32 v23, v23
	s_nop 0
	v_mul_f32_e32 v6, v6, v22
	v_mul_f32_e32 v7, v7, v23
	ds_write_b32 v152, v6 offset:4096
	ds_write_b32 v152, v7 offset:6144
	s_waitcnt vmcnt(10)
	v_mul_f32_e32 v22, 0xbfb8aa3b, v8
	v_mul_f32_e32 v23, 0xbfb8aa3b, v9
	v_exp_f32_e32 v22, v22
	v_exp_f32_e32 v23, v23
	s_nop 0
	v_add_f32_e32 v22, 1.0, v22
	v_add_f32_e32 v23, 1.0, v23
	v_rcp_f32_e32 v22, v22
	v_rcp_f32_e32 v23, v23
	s_nop 0
	v_mul_f32_e32 v8, v8, v22
	v_mul_f32_e32 v9, v9, v23
	ds_write_b32 v152, v8 offset:8192
	ds_write_b32 v152, v9 offset:10240
	s_waitcnt vmcnt(8)
	v_mul_f32_e32 v22, 0xbfb8aa3b, v10
	v_mul_f32_e32 v23, 0xbfb8aa3b, v11
	v_exp_f32_e32 v22, v22
	v_exp_f32_e32 v23, v23
	s_nop 0
	v_add_f32_e32 v22, 1.0, v22
	v_add_f32_e32 v23, 1.0, v23
	v_rcp_f32_e32 v22, v22
	v_rcp_f32_e32 v23, v23
	s_nop 0
	v_mul_f32_e32 v10, v10, v22
	v_mul_f32_e32 v11, v11, v23
	ds_write_b32 v152, v10 offset:12288
	ds_write_b32 v152, v11 offset:14336
	s_waitcnt vmcnt(6)
	v_mul_f32_e32 v22, 0xbfb8aa3b, v12
	v_mul_f32_e32 v23, 0xbfb8aa3b, v13
	v_exp_f32_e32 v22, v22
	v_exp_f32_e32 v23, v23
	s_nop 0
	v_add_f32_e32 v22, 1.0, v22
	v_add_f32_e32 v23, 1.0, v23
	v_rcp_f32_e32 v22, v22
	v_rcp_f32_e32 v23, v23
	s_nop 0
	v_mul_f32_e32 v12, v12, v22
	v_mul_f32_e32 v13, v13, v23
	ds_write_b32 v152, v12 offset:16384
	ds_write_b32 v152, v13 offset:18432
	s_waitcnt vmcnt(4)
	v_mul_f32_e32 v22, 0xbfb8aa3b, v14
	v_mul_f32_e32 v23, 0xbfb8aa3b, v15
	v_exp_f32_e32 v22, v22
	v_exp_f32_e32 v23, v23
	s_nop 0
	v_add_f32_e32 v22, 1.0, v22
	v_add_f32_e32 v23, 1.0, v23
	v_rcp_f32_e32 v22, v22
	v_rcp_f32_e32 v23, v23
	s_nop 0
	v_mul_f32_e32 v14, v14, v22
	v_mul_f32_e32 v15, v15, v23
	ds_write_b32 v152, v14 offset:20480
	ds_write_b32 v152, v15 offset:22528
	s_waitcnt vmcnt(2)
	v_mul_f32_e32 v22, 0xbfb8aa3b, v16
	v_mul_f32_e32 v23, 0xbfb8aa3b, v17
	v_exp_f32_e32 v22, v22
	v_exp_f32_e32 v23, v23
	s_nop 0
	v_add_f32_e32 v22, 1.0, v22
	v_add_f32_e32 v23, 1.0, v23
	v_rcp_f32_e32 v22, v22
	v_rcp_f32_e32 v23, v23
	s_nop 0
	v_mul_f32_e32 v16, v16, v22
	v_mul_f32_e32 v17, v17, v23
	ds_write_b32 v152, v16 offset:24576
	ds_write_b32 v152, v17 offset:26624
	s_waitcnt vmcnt(0)
	v_mul_f32_e32 v22, 0xbfb8aa3b, v18
	v_mul_f32_e32 v23, 0xbfb8aa3b, v19
	v_exp_f32_e32 v22, v22
	v_exp_f32_e32 v23, v23
	s_nop 0
	v_add_f32_e32 v22, 1.0, v22
	v_add_f32_e32 v23, 1.0, v23
	v_rcp_f32_e32 v22, v22
	v_rcp_f32_e32 v23, v23
	s_nop 0
	v_mul_f32_e32 v18, v18, v22
	v_mul_f32_e32 v19, v19, v23
	ds_write_b32 v152, v18 offset:28672
	ds_write_b32 v152, v19 offset:30720

.LBB0_111:
	s_cmp_lt_i32 s56, 2
	s_cselect_b64 s[8:9], -1, 0
	s_and_b64 s[0:1], s[8:9], s[0:1]
	s_andn2_b64 vcc, exec, s[0:1]
	s_cbranch_vccnz .LBB0_130
	v_mbcnt_lo_u32_b32 v0, -1, 0
	v_mbcnt_hi_u32_b32 v164, -1, v0
	s_and_b32 s0, s85, 0xffffffc0
	v_add_u32_e32 v0, s0, v164
	s_movk_i32 s0, 0x2000
	v_cmp_gt_i32_e32 vcc, s0, v0
	s_and_saveexec_b64 s[0:1], vcc
	s_cbranch_execz .LBB0_124
	s_waitcnt lgkmcnt(0)
	v_lshrrev_b32_e32 v1, 3, v0
	v_and_b32_e32 v2, 7, v0
	v_mul_u32_u24_e32 v3, 0x1008, v1
	v_add_u32_e32 v3, v3, v2
	v_add_u32_e32 v3, 0x1000, v3
	v_lshlrev_b32_e32 v4, 2, v3
	v_mov_b32_e32 v5, 0
	v_lshl_add_u64 v[4:5], s[46:47], 0, v[4:5]
	v_lshlrev_b32_e32 v6, 12, v2
	v_lshl_add_u32 v6, v1, 2, v6
	s_mov_b32 s98, 0x100800
	s_mov_b32 s99, 0
	global_load_dword v8, v[4:5], off
	v_lshl_add_u64 v[4:5], v[4:5], 0, s[98:99]
	global_load_dword v9, v[4:5], off
	v_lshl_add_u64 v[4:5], v[4:5], 0, s[98:99]
	global_load_dword v10, v[4:5], off
	v_lshl_add_u64 v[4:5], v[4:5], 0, s[98:99]
	global_load_dword v11, v[4:5], off
	v_lshl_add_u64 v[4:5], v[4:5], 0, s[98:99]
	global_load_dword v12, v[4:5], off
	v_lshl_add_u64 v[4:5], v[4:5], 0, s[98:99]
	global_load_dword v13, v[4:5], off
	v_lshl_add_u64 v[4:5], v[4:5], 0, s[98:99]
	global_load_dword v14, v[4:5], off
	v_lshl_add_u64 v[4:5], v[4:5], 0, s[98:99]
	global_load_dword v15, v[4:5], off
	v_lshl_add_u64 v[4:5], v[4:5], 0, s[98:99]
	global_load_dword v16, v[4:5], off
	v_lshl_add_u64 v[4:5], v[4:5], 0, s[98:99]
	global_load_dword v17, v[4:5], off
	v_lshl_add_u64 v[4:5], v[4:5], 0, s[98:99]
	global_load_dword v18, v[4:5], off
	v_lshl_add_u64 v[4:5], v[4:5], 0, s[98:99]
	global_load_dword v19, v[4:5], off
	v_lshl_add_u64 v[4:5], v[4:5], 0, s[98:99]
	global_load_dword v20, v[4:5], off
	v_lshl_add_u64 v[4:5], v[4:5], 0, s[98:99]
	global_load_dword v21, v[4:5], off
	v_lshl_add_u64 v[4:5], v[4:5], 0, s[98:99]
	global_load_dword v22, v[4:5], off
	v_lshl_add_u64 v[4:5], v[4:5], 0, s[98:99]
	global_load_dword v23, v[4:5], off
	s_waitcnt vmcnt(15)
	ds_write_b32 v6, v8 offset:0
	s_waitcnt vmcnt(14)
	ds_write_b32 v6, v9 offset:256
	s_waitcnt vmcnt(13)
	ds_write_b32 v6, v10 offset:512
	s_waitcnt vmcnt(12)
	ds_write_b32 v6, v11 offset:768
	s_waitcnt vmcnt(11)
	ds_write_b32 v6, v12 offset:1024
	s_waitcnt vmcnt(10)
	ds_write_b32 v6, v13 offset:1280
	s_waitcnt vmcnt(9)
	ds_write_b32 v6, v14 offset:1536
	s_waitcnt vmcnt(8)
	ds_write_b32 v6, v15 offset:1792
	s_waitcnt vmcnt(7)
	ds_write_b32 v6, v16 offset:2048
	s_waitcnt vmcnt(6)
	ds_write_b32 v6, v17 offset:2304
	s_waitcnt vmcnt(5)
	ds_write_b32 v6, v18 offset:2560
	s_waitcnt vmcnt(4)
	ds_write_b32 v6, v19 offset:2816
	s_waitcnt vmcnt(3)
	ds_write_b32 v6, v20 offset:3072
	s_waitcnt vmcnt(2)
	ds_write_b32 v6, v21 offset:3328
	s_waitcnt vmcnt(1)
	ds_write_b32 v6, v22 offset:3584
	s_waitcnt vmcnt(0)
	ds_write_b32 v6, v23 offset:3840
